# weight transposes read the once-used f32 weights with nt (non-temporal) loads
# speedup vs baseline: 1.0118x; 1.0090x over previous
.Lptr_dec1_done:
	v_mul_lo_u32 v123, v112, s76
	v_add_u32_e32 v118, v123, v113
	s_lshl_b32 vcc_lo, s76, 5
	v_add_u32_e32 v119, vcc_lo, v118
	v_add_u32_e32 v120, vcc_lo, v119
	v_add_u32_e32 v121, vcc_lo, v120
	global_load_dwordx4 v[40:43], v118, s[30:31] nt
	global_load_dwordx4 v[44:47], v119, s[30:31] nt
	global_load_dwordx4 v[48:51], v120, s[30:31] nt
	global_load_dwordx4 v[52:55], v121, s[30:31] nt
	s_mul_i32 s48, s81, 1
	s_add_u32 s48, s48, s39
	s_min_u32 s48, s48, s84
	s_sub_u32 s0, s48, 0x80
	s_cmpk_lt_u32 s0, 0x80
	s_cbranch_scc1 .Lptr_dec2_br
	s_cmpk_lt_u32 s0, 0x100
	s_cbranch_scc1 .Lptr_dec2_out
	s_cmpk_lt_u32 s0, 0x3c0
	s_cbranch_scc1 .Lptr_dec2_up
	s_sub_u32 s0, s0, 0x3c0
	s_lshr_b32 s2, s0, 4
	s_and_b32 s3, s0, 15
	s_lshl_b32 s12, s2, 19
	s_lshl_b32 s13, s3, 8
	s_add_u32 s12, s12, s13
	s_add_u32 s30, s21, s12
	s_addc_u32 s31, s68, 0
	s_mul_i32 s12, s3, 0x58000
	s_lshl_b32 s13, s2, 8
	s_add_u32 s12, s12, s13
	s_add_u32 s74, s6, s12
	s_addc_u32 s75, s7, 0
	s_movk_i32 s76, 0x1000
	s_movk_i32 s86, 0x1600
	s_branch .Lptr_dec2_done

.Lptr_dec2_done:
	v_mul_lo_u32 v123, v112, s76
	v_add_u32_e32 v118, v123, v113
	s_lshl_b32 vcc_lo, s76, 5
	v_add_u32_e32 v119, vcc_lo, v118
	v_add_u32_e32 v120, vcc_lo, v119
	v_add_u32_e32 v121, vcc_lo, v120
	global_load_dwordx4 v[56:59], v118, s[30:31] nt
	global_load_dwordx4 v[60:63], v119, s[30:31] nt
	global_load_dwordx4 v[64:67], v120, s[30:31] nt
	global_load_dwordx4 v[68:71], v121, s[30:31] nt
	s_mul_i32 s48, s81, 2
	s_add_u32 s48, s48, s39
	s_min_u32 s48, s48, s84
	s_sub_u32 s0, s48, 0x80
	s_cmpk_lt_u32 s0, 0x80
	s_cbranch_scc1 .Lptr_dec3_br
	s_cmpk_lt_u32 s0, 0x100
	s_cbranch_scc1 .Lptr_dec3_out
	s_cmpk_lt_u32 s0, 0x3c0
	s_cbranch_scc1 .Lptr_dec3_up
	s_sub_u32 s0, s0, 0x3c0
	s_lshr_b32 s2, s0, 4
	s_and_b32 s3, s0, 15
	s_lshl_b32 s12, s2, 19
	s_lshl_b32 s13, s3, 8
	s_add_u32 s12, s12, s13
	s_add_u32 s30, s21, s12
	s_addc_u32 s31, s68, 0
	s_mul_i32 s12, s3, 0x58000
	s_lshl_b32 s13, s2, 8
	s_add_u32 s12, s12, s13
	s_add_u32 s74, s6, s12
	s_addc_u32 s75, s7, 0
	s_movk_i32 s76, 0x1000
	s_movk_i32 s86, 0x1600
	s_branch .Lptr_dec3_done

.Lptr_dec3_done:
	v_mul_lo_u32 v123, v112, s76
	v_add_u32_e32 v118, v123, v113
	s_lshl_b32 vcc_lo, s76, 5
	v_add_u32_e32 v119, vcc_lo, v118
	v_add_u32_e32 v120, vcc_lo, v119
	v_add_u32_e32 v121, vcc_lo, v120
	global_load_dwordx4 v[72:75], v118, s[30:31] nt
	global_load_dwordx4 v[76:79], v119, s[30:31] nt
	global_load_dwordx4 v[80:83], v120, s[30:31] nt
	global_load_dwordx4 v[84:87], v121, s[30:31] nt
	s_mul_i32 s48, s81, 3
	s_add_u32 s48, s48, s39
	s_min_u32 s48, s48, s84
	s_sub_u32 s0, s48, 0x80
	s_cmpk_lt_u32 s0, 0x80
	s_cbranch_scc1 .Lptr_dec4_br
	s_cmpk_lt_u32 s0, 0x100
	s_cbranch_scc1 .Lptr_dec4_out
	s_cmpk_lt_u32 s0, 0x3c0
	s_cbranch_scc1 .Lptr_dec4_up
	s_sub_u32 s0, s0, 0x3c0
	s_lshr_b32 s2, s0, 4
	s_and_b32 s3, s0, 15
	s_lshl_b32 s12, s2, 19
	s_lshl_b32 s13, s3, 8
	s_add_u32 s12, s12, s13
	s_add_u32 s30, s21, s12
	s_addc_u32 s31, s68, 0
	s_mul_i32 s12, s3, 0x58000
	s_lshl_b32 s13, s2, 8
	s_add_u32 s12, s12, s13
	s_add_u32 s74, s6, s12
	s_addc_u32 s75, s7, 0
	s_movk_i32 s76, 0x1000
	s_movk_i32 s86, 0x1600
	s_branch .Lptr_dec4_done

.Lptr_dec4_done:
	v_mul_lo_u32 v123, v112, s76
	v_add_u32_e32 v118, v123, v113
	s_lshl_b32 vcc_lo, s76, 5
	v_add_u32_e32 v119, vcc_lo, v118
	v_add_u32_e32 v120, vcc_lo, v119
	v_add_u32_e32 v121, vcc_lo, v120
	global_load_dwordx4 v[124:127], v118, s[30:31] nt
	global_load_dwordx4 v[128:131], v119, s[30:31] nt
	global_load_dwordx4 v[132:135], v120, s[30:31] nt
	global_load_dwordx4 v[136:139], v121, s[30:31] nt
	s_waitcnt vmcnt(12)
	ds_write_b32 v114, v40 offset:0
	ds_write_b32 v114, v41 offset:4
	ds_write_b32 v114, v42 offset:8
	ds_write_b32 v114, v43 offset:12
	ds_write_b32 v114, v44 offset:8320
	ds_write_b32 v114, v45 offset:8324
	ds_write_b32 v114, v46 offset:8328
	ds_write_b32 v114, v47 offset:8332
	ds_write_b32 v114, v48 offset:16640
	ds_write_b32 v114, v49 offset:16644
	ds_write_b32 v114, v50 offset:16648
	ds_write_b32 v114, v51 offset:16652
	ds_write_b32 v114, v52 offset:24960
	ds_write_b32 v114, v53 offset:24964
	ds_write_b32 v114, v54 offset:24968
	ds_write_b32 v114, v55 offset:24972
	s_waitcnt lgkmcnt(0)
	s_barrier
	ds_read_b32 v88, v115 offset:0
	ds_read_b32 v89, v115 offset:260
	ds_read_b32 v90, v115 offset:520
	ds_read_b32 v91, v115 offset:780
	ds_read_b32 v92, v115 offset:1040
	ds_read_b32 v93, v115 offset:1300
	ds_read_b32 v94, v115 offset:1560
	ds_read_b32 v95, v115 offset:1820
	ds_read_b32 v96, v115 offset:2080
	ds_read_b32 v97, v115 offset:2340
	ds_read_b32 v98, v115 offset:2600
	ds_read_b32 v99, v115 offset:2860
	ds_read_b32 v100, v115 offset:3120
	ds_read_b32 v101, v115 offset:3380
	ds_read_b32 v102, v115 offset:3640
	ds_read_b32 v103, v115 offset:3900
	s_mul_i32 s48, s81, 0
	s_add_u32 s48, s48, s39
	s_min_u32 s48, s48, s84
	s_sub_u32 s0, s48, 0x80
	s_cmpk_lt_u32 s0, 0x80
	s_cbranch_scc1 .Lptr_dec5_br
	s_cmpk_lt_u32 s0, 0x100
	s_cbranch_scc1 .Lptr_dec5_out
	s_cmpk_lt_u32 s0, 0x3c0
	s_cbranch_scc1 .Lptr_dec5_up
	s_sub_u32 s0, s0, 0x3c0
	s_lshr_b32 s2, s0, 4
	s_and_b32 s3, s0, 15
	s_lshl_b32 s12, s2, 19
	s_lshl_b32 s13, s3, 8
	s_add_u32 s12, s12, s13
	s_add_u32 s30, s21, s12
	s_addc_u32 s31, s68, 0
	s_mul_i32 s12, s3, 0x58000
	s_lshl_b32 s13, s2, 8
	s_add_u32 s12, s12, s13
	s_add_u32 s74, s6, s12
	s_addc_u32 s75, s7, 0
	s_movk_i32 s76, 0x1000
	s_movk_i32 s86, 0x1600
	s_branch .Lptr_dec5_done

.Lptr_dec6_done:
	v_mul_lo_u32 v123, v112, s76
	v_add_u32_e32 v118, v123, v113
	s_lshl_b32 vcc_lo, s76, 5
	v_add_u32_e32 v119, vcc_lo, v118
	v_add_u32_e32 v120, vcc_lo, v119
	v_add_u32_e32 v121, vcc_lo, v120
	global_load_dwordx4 v[40:43], v118, s[30:31] nt
	global_load_dwordx4 v[44:47], v119, s[30:31] nt
	global_load_dwordx4 v[48:51], v120, s[30:31] nt
	global_load_dwordx4 v[52:55], v121, s[30:31] nt
	s_waitcnt vmcnt(14)
	ds_write_b32 v114, v56 offset:33792
	ds_write_b32 v114, v57 offset:33796
	ds_write_b32 v114, v58 offset:33800
	ds_write_b32 v114, v59 offset:33804
	ds_write_b32 v114, v60 offset:42112
	ds_write_b32 v114, v61 offset:42116
	ds_write_b32 v114, v62 offset:42120
	ds_write_b32 v114, v63 offset:42124
	ds_write_b32 v114, v64 offset:50432
	ds_write_b32 v114, v65 offset:50436
	ds_write_b32 v114, v66 offset:50440
	ds_write_b32 v114, v67 offset:50444
	ds_write_b32 v114, v68 offset:58752
	ds_write_b32 v114, v69 offset:58756
	ds_write_b32 v114, v70 offset:58760
	ds_write_b32 v114, v71 offset:58764
	s_waitcnt lgkmcnt(0)
	s_barrier
	ds_read_b32 v88, v115 offset:33792
	ds_read_b32 v89, v115 offset:34052
	ds_read_b32 v90, v115 offset:34312
	ds_read_b32 v91, v115 offset:34572
	ds_read_b32 v92, v115 offset:34832
	ds_read_b32 v93, v115 offset:35092
	ds_read_b32 v94, v115 offset:35352
	ds_read_b32 v95, v115 offset:35612
	ds_read_b32 v96, v115 offset:35872
	ds_read_b32 v97, v115 offset:36132
	ds_read_b32 v98, v115 offset:36392
	ds_read_b32 v99, v115 offset:36652
	ds_read_b32 v100, v115 offset:36912
	ds_read_b32 v101, v115 offset:37172
	ds_read_b32 v102, v115 offset:37432
	ds_read_b32 v103, v115 offset:37692
	s_mul_i32 s48, s81, 1
	s_add_u32 s48, s48, s39
	s_min_u32 s48, s48, s84
	s_sub_u32 s0, s48, 0x80
	s_cmpk_lt_u32 s0, 0x80
	s_cbranch_scc1 .Lptr_dec7_br
	s_cmpk_lt_u32 s0, 0x100
	s_cbranch_scc1 .Lptr_dec7_out
	s_cmpk_lt_u32 s0, 0x3c0
	s_cbranch_scc1 .Lptr_dec7_up
	s_sub_u32 s0, s0, 0x3c0
	s_lshr_b32 s2, s0, 4
	s_and_b32 s3, s0, 15
	s_lshl_b32 s12, s2, 19
	s_lshl_b32 s13, s3, 8
	s_add_u32 s12, s12, s13
	s_add_u32 s30, s21, s12
	s_addc_u32 s31, s68, 0
	s_mul_i32 s12, s3, 0x58000
	s_lshl_b32 s13, s2, 8
	s_add_u32 s12, s12, s13
	s_add_u32 s74, s6, s12
	s_addc_u32 s75, s7, 0
	s_movk_i32 s76, 0x1000
	s_movk_i32 s86, 0x1600
	s_branch .Lptr_dec7_done

.Lptr_dec8_done:
	v_mul_lo_u32 v123, v112, s76
	v_add_u32_e32 v118, v123, v113
	s_lshl_b32 vcc_lo, s76, 5
	v_add_u32_e32 v119, vcc_lo, v118
	v_add_u32_e32 v120, vcc_lo, v119
	v_add_u32_e32 v121, vcc_lo, v120
	global_load_dwordx4 v[56:59], v118, s[30:31] nt
	global_load_dwordx4 v[60:63], v119, s[30:31] nt
	global_load_dwordx4 v[64:67], v120, s[30:31] nt
	global_load_dwordx4 v[68:71], v121, s[30:31] nt
	s_waitcnt vmcnt(16)
	ds_write_b32 v114, v72 offset:0
	ds_write_b32 v114, v73 offset:4
	ds_write_b32 v114, v74 offset:8
	ds_write_b32 v114, v75 offset:12
	ds_write_b32 v114, v76 offset:8320
	ds_write_b32 v114, v77 offset:8324
	ds_write_b32 v114, v78 offset:8328
	ds_write_b32 v114, v79 offset:8332
	ds_write_b32 v114, v80 offset:16640
	ds_write_b32 v114, v81 offset:16644
	ds_write_b32 v114, v82 offset:16648
	ds_write_b32 v114, v83 offset:16652
	ds_write_b32 v114, v84 offset:24960
	ds_write_b32 v114, v85 offset:24964
	ds_write_b32 v114, v86 offset:24968
	ds_write_b32 v114, v87 offset:24972
	s_waitcnt lgkmcnt(0)
	s_barrier
	ds_read_b32 v88, v115 offset:0
	ds_read_b32 v89, v115 offset:260
	ds_read_b32 v90, v115 offset:520
	ds_read_b32 v91, v115 offset:780
	ds_read_b32 v92, v115 offset:1040
	ds_read_b32 v93, v115 offset:1300
	ds_read_b32 v94, v115 offset:1560
	ds_read_b32 v95, v115 offset:1820
	ds_read_b32 v96, v115 offset:2080
	ds_read_b32 v97, v115 offset:2340
	ds_read_b32 v98, v115 offset:2600
	ds_read_b32 v99, v115 offset:2860
	ds_read_b32 v100, v115 offset:3120
	ds_read_b32 v101, v115 offset:3380
	ds_read_b32 v102, v115 offset:3640
	ds_read_b32 v103, v115 offset:3900
	s_mul_i32 s48, s81, 2
	s_add_u32 s48, s48, s39
	s_min_u32 s48, s48, s84
	s_sub_u32 s0, s48, 0x80
	s_cmpk_lt_u32 s0, 0x80
	s_cbranch_scc1 .Lptr_dec9_br
	s_cmpk_lt_u32 s0, 0x100
	s_cbranch_scc1 .Lptr_dec9_out
	s_cmpk_lt_u32 s0, 0x3c0
	s_cbranch_scc1 .Lptr_dec9_up
	s_sub_u32 s0, s0, 0x3c0
	s_lshr_b32 s2, s0, 4
	s_and_b32 s3, s0, 15
	s_lshl_b32 s12, s2, 19
	s_lshl_b32 s13, s3, 8
	s_add_u32 s12, s12, s13
	s_add_u32 s30, s21, s12
	s_addc_u32 s31, s68, 0
	s_mul_i32 s12, s3, 0x58000
	s_lshl_b32 s13, s2, 8
	s_add_u32 s12, s12, s13
	s_add_u32 s74, s6, s12
	s_addc_u32 s75, s7, 0
	s_movk_i32 s76, 0x1000
	s_movk_i32 s86, 0x1600
	s_branch .Lptr_dec9_done

.Lptr_dec10_done:
	v_mul_lo_u32 v123, v112, s76
	v_add_u32_e32 v118, v123, v113
	s_lshl_b32 vcc_lo, s76, 5
	v_add_u32_e32 v119, vcc_lo, v118
	v_add_u32_e32 v120, vcc_lo, v119
	v_add_u32_e32 v121, vcc_lo, v120
	global_load_dwordx4 v[72:75], v118, s[30:31] nt
	global_load_dwordx4 v[76:79], v119, s[30:31] nt
	global_load_dwordx4 v[80:83], v120, s[30:31] nt
	global_load_dwordx4 v[84:87], v121, s[30:31] nt
	s_waitcnt vmcnt(18)
	ds_write_b32 v114, v124 offset:33792
	ds_write_b32 v114, v125 offset:33796
	ds_write_b32 v114, v126 offset:33800
	ds_write_b32 v114, v127 offset:33804
	ds_write_b32 v114, v128 offset:42112
	ds_write_b32 v114, v129 offset:42116
	ds_write_b32 v114, v130 offset:42120
	ds_write_b32 v114, v131 offset:42124
	ds_write_b32 v114, v132 offset:50432
	ds_write_b32 v114, v133 offset:50436
	ds_write_b32 v114, v134 offset:50440
	ds_write_b32 v114, v135 offset:50444
	ds_write_b32 v114, v136 offset:58752
	ds_write_b32 v114, v137 offset:58756
	ds_write_b32 v114, v138 offset:58760
	ds_write_b32 v114, v139 offset:58764
	s_waitcnt lgkmcnt(0)
	s_barrier
	ds_read_b32 v88, v115 offset:33792
	ds_read_b32 v89, v115 offset:34052
	ds_read_b32 v90, v115 offset:34312
	ds_read_b32 v91, v115 offset:34572
	ds_read_b32 v92, v115 offset:34832
	ds_read_b32 v93, v115 offset:35092
	ds_read_b32 v94, v115 offset:35352
	ds_read_b32 v95, v115 offset:35612
	ds_read_b32 v96, v115 offset:35872
	ds_read_b32 v97, v115 offset:36132
	ds_read_b32 v98, v115 offset:36392
	ds_read_b32 v99, v115 offset:36652
	ds_read_b32 v100, v115 offset:36912
	ds_read_b32 v101, v115 offset:37172
	ds_read_b32 v102, v115 offset:37432
	ds_read_b32 v103, v115 offset:37692
	s_mul_i32 s48, s81, 3
	s_add_u32 s48, s48, s39
	s_min_u32 s48, s48, s84
	s_sub_u32 s0, s48, 0x80
	s_cmpk_lt_u32 s0, 0x80
	s_cbranch_scc1 .Lptr_dec11_br
	s_cmpk_lt_u32 s0, 0x100
	s_cbranch_scc1 .Lptr_dec11_out
	s_cmpk_lt_u32 s0, 0x3c0
	s_cbranch_scc1 .Lptr_dec11_up
	s_sub_u32 s0, s0, 0x3c0
	s_lshr_b32 s2, s0, 4
	s_and_b32 s3, s0, 15
	s_lshl_b32 s12, s2, 19
	s_lshl_b32 s13, s3, 8
	s_add_u32 s12, s12, s13
	s_add_u32 s30, s21, s12
	s_addc_u32 s31, s68, 0
	s_mul_i32 s12, s3, 0x58000
	s_lshl_b32 s13, s2, 8
	s_add_u32 s12, s12, s13
	s_add_u32 s74, s6, s12
	s_addc_u32 s75, s7, 0
	s_movk_i32 s76, 0x1000
	s_movk_i32 s86, 0x1600
	s_branch .Lptr_dec11_done

.Ln1t_kdone:
	v_lshrrev_b32_e32 v112, 4, v1
	v_and_b32_e32 v113, 15, v1
	v_lshlrev_b32_e32 v113, 4, v113
	v_mul_u32_u24_e32 v114, 0x104, v112
	v_add_u32_e32 v114, v114, v113
	v_lshrrev_b32_e32 v116, 3, v1
	v_and_b32_e32 v117, 7, v1
	v_mul_u32_u24_e32 v115, 0x1040, v117
	v_lshl_add_u32 v115, v116, 2, v115
	v_lshlrev_b32_e32 v117, 5, v117
	s_mul_i32 s48, s73, 0
	s_add_u32 s48, s48, s74
	s_min_u32 s48, s48, s72
	s_mov_b32 s0, s48
	s_mul_i32 s2, s0, 0x4ed
	s_lshr_b32 s2, s2, 17
	s_mul_i32 s3, s2, 0x68
	s_sub_u32 s3, s0, s3
	s_mul_i32 s14, s2, 0x340000
	s_lshl_b32 s0, s3, 8
	s_add_u32 s14, s14, s0
	s_add_u32 s6, s68, s14
	s_addc_u32 s7, s69, 0
	s_lshl_b32 s14, s3, 17
	s_lshl_b32 s0, s2, 8
	s_add_u32 s14, s14, s0
	s_add_u32 s8, s70, s14
	s_addc_u32 s9, s71, 0
	s_movk_i32 s12, 0x6800
	s_movk_i32 s13, 0x800
	v_mul_lo_u32 v123, v112, s12
	v_add_u32_e32 v118, v123, v113
	s_lshl_b32 vcc_lo, s12, 5
	v_add_u32_e32 v119, vcc_lo, v118
	v_add_u32_e32 v120, vcc_lo, v119
	v_add_u32_e32 v121, vcc_lo, v120
	global_load_dwordx4 v[40:43], v118, s[6:7] nt
	global_load_dwordx4 v[44:47], v119, s[6:7] nt
	global_load_dwordx4 v[48:51], v120, s[6:7] nt
	global_load_dwordx4 v[52:55], v121, s[6:7] nt
	s_mul_i32 s48, s73, 1
	s_add_u32 s48, s48, s74
	s_min_u32 s48, s48, s72
	s_mov_b32 s0, s48
	s_mul_i32 s2, s0, 0x4ed
	s_lshr_b32 s2, s2, 17
	s_mul_i32 s3, s2, 0x68
	s_sub_u32 s3, s0, s3
	s_mul_i32 s14, s2, 0x340000
	s_lshl_b32 s0, s3, 8
	s_add_u32 s14, s14, s0
	s_add_u32 s6, s68, s14
	s_addc_u32 s7, s69, 0
	s_lshl_b32 s14, s3, 17
	s_lshl_b32 s0, s2, 8
	s_add_u32 s14, s14, s0
	s_add_u32 s8, s70, s14
	s_addc_u32 s9, s71, 0
	s_movk_i32 s12, 0x6800
	s_movk_i32 s13, 0x800
	v_mul_lo_u32 v123, v112, s12
	v_add_u32_e32 v118, v123, v113
	s_lshl_b32 vcc_lo, s12, 5
	v_add_u32_e32 v119, vcc_lo, v118
	v_add_u32_e32 v120, vcc_lo, v119
	v_add_u32_e32 v121, vcc_lo, v120
	global_load_dwordx4 v[56:59], v118, s[6:7] nt
	global_load_dwordx4 v[60:63], v119, s[6:7] nt
	global_load_dwordx4 v[64:67], v120, s[6:7] nt
	global_load_dwordx4 v[68:71], v121, s[6:7] nt
	s_waitcnt vmcnt(4)
	ds_write_b32 v114, v40 offset:0
	ds_write_b32 v114, v41 offset:4
	ds_write_b32 v114, v42 offset:8
	ds_write_b32 v114, v43 offset:12
	ds_write_b32 v114, v44 offset:8320
	ds_write_b32 v114, v45 offset:8324
	ds_write_b32 v114, v46 offset:8328
	ds_write_b32 v114, v47 offset:8332
	ds_write_b32 v114, v48 offset:16640
	ds_write_b32 v114, v49 offset:16644
	ds_write_b32 v114, v50 offset:16648
	ds_write_b32 v114, v51 offset:16652
	ds_write_b32 v114, v52 offset:24960
	ds_write_b32 v114, v53 offset:24964
	ds_write_b32 v114, v54 offset:24968
	ds_write_b32 v114, v55 offset:24972
	s_waitcnt lgkmcnt(0)
	s_barrier
	ds_read_b32 v88, v115 offset:0
	ds_read_b32 v89, v115 offset:260
	ds_read_b32 v90, v115 offset:520
	ds_read_b32 v91, v115 offset:780
	ds_read_b32 v92, v115 offset:1040
	ds_read_b32 v93, v115 offset:1300
	ds_read_b32 v94, v115 offset:1560
	ds_read_b32 v95, v115 offset:1820
	ds_read_b32 v96, v115 offset:2080
	ds_read_b32 v97, v115 offset:2340
	ds_read_b32 v98, v115 offset:2600
	ds_read_b32 v99, v115 offset:2860
	ds_read_b32 v100, v115 offset:3120
	ds_read_b32 v101, v115 offset:3380
	ds_read_b32 v102, v115 offset:3640
	ds_read_b32 v103, v115 offset:3900
	s_mul_i32 s48, s73, 0
	s_add_u32 s48, s48, s74
	s_min_u32 s48, s48, s72
	s_mov_b32 s0, s48
	s_mul_i32 s2, s0, 0x4ed
	s_lshr_b32 s2, s2, 17
	s_mul_i32 s3, s2, 0x68
	s_sub_u32 s3, s0, s3
	s_mul_i32 s14, s2, 0x340000
	s_lshl_b32 s0, s3, 8
	s_add_u32 s14, s14, s0
	s_add_u32 s6, s68, s14
	s_addc_u32 s7, s69, 0
	s_lshl_b32 s14, s3, 17
	s_lshl_b32 s0, s2, 8
	s_add_u32 s14, s14, s0
	s_add_u32 s8, s70, s14
	s_addc_u32 s9, s71, 0
	s_movk_i32 s12, 0x6800
	s_movk_i32 s13, 0x800
	v_mul_lo_u32 v122, v116, s13
	v_add_u32_e32 v122, v122, v117
	s_waitcnt lgkmcnt(0)
	v_cvt_pk_bf16_f32 v104, v88, v89
	v_cvt_pk_bf16_f32 v105, v90, v91
	v_cvt_pk_bf16_f32 v106, v92, v93
	v_cvt_pk_bf16_f32 v107, v94, v95
	v_cvt_pk_bf16_f32 v108, v96, v97
	v_cvt_pk_bf16_f32 v109, v98, v99
	v_cvt_pk_bf16_f32 v110, v100, v101
	v_cvt_pk_bf16_f32 v111, v102, v103
	global_store_dwordx4 v122, v[104:107], s[8:9]
	global_store_dwordx4 v122, v[108:111], s[8:9] offset:16
	s_nop 1
	s_waitcnt vmcnt(2)
	ds_write_b32 v114, v56 offset:33792
	ds_write_b32 v114, v57 offset:33796
	ds_write_b32 v114, v58 offset:33800
	ds_write_b32 v114, v59 offset:33804
	ds_write_b32 v114, v60 offset:42112
	ds_write_b32 v114, v61 offset:42116
	ds_write_b32 v114, v62 offset:42120
	ds_write_b32 v114, v63 offset:42124
	ds_write_b32 v114, v64 offset:50432
	ds_write_b32 v114, v65 offset:50436
	ds_write_b32 v114, v66 offset:50440
	ds_write_b32 v114, v67 offset:50444
	ds_write_b32 v114, v68 offset:58752
	ds_write_b32 v114, v69 offset:58756
	ds_write_b32 v114, v70 offset:58760
	ds_write_b32 v114, v71 offset:58764
	s_waitcnt lgkmcnt(0)
	s_barrier
	ds_read_b32 v88, v115 offset:33792
	ds_read_b32 v89, v115 offset:34052
	ds_read_b32 v90, v115 offset:34312
	ds_read_b32 v91, v115 offset:34572
	ds_read_b32 v92, v115 offset:34832
	ds_read_b32 v93, v115 offset:35092
	ds_read_b32 v94, v115 offset:35352
	ds_read_b32 v95, v115 offset:35612
	ds_read_b32 v96, v115 offset:35872
	ds_read_b32 v97, v115 offset:36132
	ds_read_b32 v98, v115 offset:36392
	ds_read_b32 v99, v115 offset:36652
	ds_read_b32 v100, v115 offset:36912
	ds_read_b32 v101, v115 offset:37172
	ds_read_b32 v102, v115 offset:37432
	ds_read_b32 v103, v115 offset:37692
	s_mul_i32 s48, s73, 1
	s_add_u32 s48, s48, s74
	s_min_u32 s48, s48, s72
	s_mov_b32 s0, s48
	s_mul_i32 s2, s0, 0x4ed
	s_lshr_b32 s2, s2, 17
	s_mul_i32 s3, s2, 0x68
	s_sub_u32 s3, s0, s3
	s_mul_i32 s14, s2, 0x340000
	s_lshl_b32 s0, s3, 8
	s_add_u32 s14, s14, s0
	s_add_u32 s6, s68, s14
	s_addc_u32 s7, s69, 0
	s_lshl_b32 s14, s3, 17
	s_lshl_b32 s0, s2, 8
	s_add_u32 s14, s14, s0
	s_add_u32 s8, s70, s14
	s_addc_u32 s9, s71, 0
	s_movk_i32 s12, 0x6800
	s_movk_i32 s13, 0x800
	v_mul_lo_u32 v122, v116, s13
	v_add_u32_e32 v122, v122, v117
	s_waitcnt lgkmcnt(0)
	v_cvt_pk_bf16_f32 v104, v88, v89
	v_cvt_pk_bf16_f32 v105, v90, v91
	v_cvt_pk_bf16_f32 v106, v92, v93
	v_cvt_pk_bf16_f32 v107, v94, v95
	v_cvt_pk_bf16_f32 v108, v96, v97
	v_cvt_pk_bf16_f32 v109, v98, v99
	v_cvt_pk_bf16_f32 v110, v100, v101
	v_cvt_pk_bf16_f32 v111, v102, v103
	global_store_dwordx4 v122, v[104:107], s[8:9]
	global_store_dwordx4 v122, v[108:111], s[8:9] offset:16
	s_nop 1
	s_waitcnt vmcnt(0)
	s_barrier
	s_branch .LBB0_692

.Lp0t_kdone:
	v_lshrrev_b32_e32 v112, 4, v1
	v_and_b32_e32 v113, 15, v1
	v_lshlrev_b32_e32 v113, 4, v113
	v_mul_u32_u24_e32 v114, 0x104, v112
	v_add_u32_e32 v114, v114, v113
	v_lshrrev_b32_e32 v116, 3, v1
	v_and_b32_e32 v117, 7, v1
	v_mul_u32_u24_e32 v115, 0x1040, v117
	v_lshl_add_u32 v115, v116, 2, v115
	v_lshlrev_b32_e32 v117, 5, v117
	s_mul_i32 s48, s85, 0
	s_add_u32 s48, s48, s86
	s_min_u32 s48, s48, s84
	s_sub_u32 s0, s48, 0xe0
	s_mul_i32 s2, s0, 0x4ed
	s_lshr_b32 s2, s2, 17
	s_mul_i32 s3, s2, 0x68
	s_sub_u32 s3, s0, s3
	s_mul_i32 s4, s2, 0x340000
	s_lshl_b32 s0, s3, 8
	s_add_u32 s4, s4, s0
	s_add_u32 s6, s80, s4
	s_addc_u32 s7, s81, 0
	s_lshl_b32 s4, s3, 17
	s_lshl_b32 s0, s2, 8
	s_add_u32 s4, s4, s0
	s_add_u32 s8, s82, s4
	s_addc_u32 s9, s83, 0
	s_movk_i32 s10, 0x6800
	s_movk_i32 s11, 0x800
	v_mul_lo_u32 v123, v112, s10
	v_add_u32_e32 v118, v123, v113
	s_lshl_b32 vcc_lo, s10, 5
	v_add_u32_e32 v119, vcc_lo, v118
	v_add_u32_e32 v120, vcc_lo, v119
	v_add_u32_e32 v121, vcc_lo, v120
	global_load_dwordx4 v[40:43], v118, s[6:7] nt
	global_load_dwordx4 v[44:47], v119, s[6:7] nt
	global_load_dwordx4 v[48:51], v120, s[6:7] nt
	global_load_dwordx4 v[52:55], v121, s[6:7] nt
	s_mul_i32 s48, s85, 1
	s_add_u32 s48, s48, s86
	s_min_u32 s48, s48, s84
	s_sub_u32 s0, s48, 0xe0
	s_mul_i32 s2, s0, 0x4ed
	s_lshr_b32 s2, s2, 17
	s_mul_i32 s3, s2, 0x68
	s_sub_u32 s3, s0, s3
	s_mul_i32 s4, s2, 0x340000
	s_lshl_b32 s0, s3, 8
	s_add_u32 s4, s4, s0
	s_add_u32 s6, s80, s4
	s_addc_u32 s7, s81, 0
	s_lshl_b32 s4, s3, 17
	s_lshl_b32 s0, s2, 8
	s_add_u32 s4, s4, s0
	s_add_u32 s8, s82, s4
	s_addc_u32 s9, s83, 0
	s_movk_i32 s10, 0x6800
	s_movk_i32 s11, 0x800
	v_mul_lo_u32 v123, v112, s10
	v_add_u32_e32 v118, v123, v113
	s_lshl_b32 vcc_lo, s10, 5
	v_add_u32_e32 v119, vcc_lo, v118
	v_add_u32_e32 v120, vcc_lo, v119
	v_add_u32_e32 v121, vcc_lo, v120
	global_load_dwordx4 v[56:59], v118, s[6:7] nt
	global_load_dwordx4 v[60:63], v119, s[6:7] nt
	global_load_dwordx4 v[64:67], v120, s[6:7] nt
	global_load_dwordx4 v[68:71], v121, s[6:7] nt
	s_mul_i32 s48, s85, 2
	s_add_u32 s48, s48, s86
	s_min_u32 s48, s48, s84
	s_sub_u32 s0, s48, 0xe0
	s_mul_i32 s2, s0, 0x4ed
	s_lshr_b32 s2, s2, 17
	s_mul_i32 s3, s2, 0x68
	s_sub_u32 s3, s0, s3
	s_mul_i32 s4, s2, 0x340000
	s_lshl_b32 s0, s3, 8
	s_add_u32 s4, s4, s0
	s_add_u32 s6, s80, s4
	s_addc_u32 s7, s81, 0
	s_lshl_b32 s4, s3, 17
	s_lshl_b32 s0, s2, 8
	s_add_u32 s4, s4, s0
	s_add_u32 s8, s82, s4
	s_addc_u32 s9, s83, 0
	s_movk_i32 s10, 0x6800
	s_movk_i32 s11, 0x800
	v_mul_lo_u32 v123, v112, s10
	v_add_u32_e32 v118, v123, v113
	s_lshl_b32 vcc_lo, s10, 5
	v_add_u32_e32 v119, vcc_lo, v118
	v_add_u32_e32 v120, vcc_lo, v119
	v_add_u32_e32 v121, vcc_lo, v120
	global_load_dwordx4 v[72:75], v118, s[6:7] nt
	global_load_dwordx4 v[76:79], v119, s[6:7] nt
	global_load_dwordx4 v[80:83], v120, s[6:7] nt
	global_load_dwordx4 v[84:87], v121, s[6:7] nt
	s_mul_i32 s48, s85, 3
	s_add_u32 s48, s48, s86
	s_min_u32 s48, s48, s84
	s_sub_u32 s0, s48, 0xe0
	s_mul_i32 s2, s0, 0x4ed
	s_lshr_b32 s2, s2, 17
	s_mul_i32 s3, s2, 0x68
	s_sub_u32 s3, s0, s3
	s_mul_i32 s4, s2, 0x340000
	s_lshl_b32 s0, s3, 8
	s_add_u32 s4, s4, s0
	s_add_u32 s6, s80, s4
	s_addc_u32 s7, s81, 0
	s_lshl_b32 s4, s3, 17
	s_lshl_b32 s0, s2, 8
	s_add_u32 s4, s4, s0
	s_add_u32 s8, s82, s4
	s_addc_u32 s9, s83, 0
	s_movk_i32 s10, 0x6800
	s_movk_i32 s11, 0x800
	v_mul_lo_u32 v123, v112, s10
	v_add_u32_e32 v118, v123, v113
	s_lshl_b32 vcc_lo, s10, 5
	v_add_u32_e32 v119, vcc_lo, v118
	v_add_u32_e32 v120, vcc_lo, v119
	v_add_u32_e32 v121, vcc_lo, v120
	global_load_dwordx4 v[124:127], v118, s[6:7] nt
	global_load_dwordx4 v[128:131], v119, s[6:7] nt
	global_load_dwordx4 v[132:135], v120, s[6:7] nt
	global_load_dwordx4 v[136:139], v121, s[6:7] nt
	s_waitcnt vmcnt(12)
	ds_write_b32 v114, v40 offset:0
	ds_write_b32 v114, v41 offset:4
	ds_write_b32 v114, v42 offset:8
	ds_write_b32 v114, v43 offset:12
	ds_write_b32 v114, v44 offset:8320
	ds_write_b32 v114, v45 offset:8324
	ds_write_b32 v114, v46 offset:8328
	ds_write_b32 v114, v47 offset:8332
	ds_write_b32 v114, v48 offset:16640
	ds_write_b32 v114, v49 offset:16644
	ds_write_b32 v114, v50 offset:16648
	ds_write_b32 v114, v51 offset:16652
	ds_write_b32 v114, v52 offset:24960
	ds_write_b32 v114, v53 offset:24964
	ds_write_b32 v114, v54 offset:24968
	ds_write_b32 v114, v55 offset:24972
	s_waitcnt lgkmcnt(0)
	s_barrier
	ds_read_b32 v88, v115 offset:0
	ds_read_b32 v89, v115 offset:260
	ds_read_b32 v90, v115 offset:520
	ds_read_b32 v91, v115 offset:780
	ds_read_b32 v92, v115 offset:1040
	ds_read_b32 v93, v115 offset:1300
	ds_read_b32 v94, v115 offset:1560
	ds_read_b32 v95, v115 offset:1820
	ds_read_b32 v96, v115 offset:2080
	ds_read_b32 v97, v115 offset:2340
	ds_read_b32 v98, v115 offset:2600
	ds_read_b32 v99, v115 offset:2860
	ds_read_b32 v100, v115 offset:3120
	ds_read_b32 v101, v115 offset:3380
	ds_read_b32 v102, v115 offset:3640
	ds_read_b32 v103, v115 offset:3900
	s_mul_i32 s48, s85, 0
	s_add_u32 s48, s48, s86
	s_min_u32 s48, s48, s84
	s_sub_u32 s0, s48, 0xe0
	s_mul_i32 s2, s0, 0x4ed
	s_lshr_b32 s2, s2, 17
	s_mul_i32 s3, s2, 0x68
	s_sub_u32 s3, s0, s3
	s_mul_i32 s4, s2, 0x340000
	s_lshl_b32 s0, s3, 8
	s_add_u32 s4, s4, s0
	s_add_u32 s6, s80, s4
	s_addc_u32 s7, s81, 0
	s_lshl_b32 s4, s3, 17
	s_lshl_b32 s0, s2, 8
	s_add_u32 s4, s4, s0
	s_add_u32 s8, s82, s4
	s_addc_u32 s9, s83, 0
	s_movk_i32 s10, 0x6800
	s_movk_i32 s11, 0x800
	v_mul_lo_u32 v122, v116, s11
	v_add_u32_e32 v122, v122, v117
	s_waitcnt lgkmcnt(0)
	v_cvt_pk_bf16_f32 v104, v88, v89
	v_cvt_pk_bf16_f32 v105, v90, v91
	v_cvt_pk_bf16_f32 v106, v92, v93
	v_cvt_pk_bf16_f32 v107, v94, v95
	v_cvt_pk_bf16_f32 v108, v96, v97
	v_cvt_pk_bf16_f32 v109, v98, v99
	v_cvt_pk_bf16_f32 v110, v100, v101
	v_cvt_pk_bf16_f32 v111, v102, v103
	global_store_dwordx4 v122, v[104:107], s[8:9]
	global_store_dwordx4 v122, v[108:111], s[8:9] offset:16
	s_nop 1
	s_waitcnt vmcnt(10)
	ds_write_b32 v114, v56 offset:33792
	ds_write_b32 v114, v57 offset:33796
	ds_write_b32 v114, v58 offset:33800
	ds_write_b32 v114, v59 offset:33804
	ds_write_b32 v114, v60 offset:42112
	ds_write_b32 v114, v61 offset:42116
	ds_write_b32 v114, v62 offset:42120
	ds_write_b32 v114, v63 offset:42124
	ds_write_b32 v114, v64 offset:50432
	ds_write_b32 v114, v65 offset:50436
	ds_write_b32 v114, v66 offset:50440
	ds_write_b32 v114, v67 offset:50444
	ds_write_b32 v114, v68 offset:58752
	ds_write_b32 v114, v69 offset:58756
	ds_write_b32 v114, v70 offset:58760
	ds_write_b32 v114, v71 offset:58764
	s_waitcnt lgkmcnt(0)
	s_barrier
	ds_read_b32 v88, v115 offset:33792
	ds_read_b32 v89, v115 offset:34052
	ds_read_b32 v90, v115 offset:34312
	ds_read_b32 v91, v115 offset:34572
	ds_read_b32 v92, v115 offset:34832
	ds_read_b32 v93, v115 offset:35092
	ds_read_b32 v94, v115 offset:35352
	ds_read_b32 v95, v115 offset:35612
	ds_read_b32 v96, v115 offset:35872
	ds_read_b32 v97, v115 offset:36132
	ds_read_b32 v98, v115 offset:36392
	ds_read_b32 v99, v115 offset:36652
	ds_read_b32 v100, v115 offset:36912
	ds_read_b32 v101, v115 offset:37172
	ds_read_b32 v102, v115 offset:37432
	ds_read_b32 v103, v115 offset:37692
	s_mul_i32 s48, s85, 1
	s_add_u32 s48, s48, s86
	s_min_u32 s48, s48, s84
	s_sub_u32 s0, s48, 0xe0
	s_mul_i32 s2, s0, 0x4ed
	s_lshr_b32 s2, s2, 17
	s_mul_i32 s3, s2, 0x68
	s_sub_u32 s3, s0, s3
	s_mul_i32 s4, s2, 0x340000
	s_lshl_b32 s0, s3, 8
	s_add_u32 s4, s4, s0
	s_add_u32 s6, s80, s4
	s_addc_u32 s7, s81, 0
	s_lshl_b32 s4, s3, 17
	s_lshl_b32 s0, s2, 8
	s_add_u32 s4, s4, s0
	s_add_u32 s8, s82, s4
	s_addc_u32 s9, s83, 0
	s_movk_i32 s10, 0x6800
	s_movk_i32 s11, 0x800
	v_mul_lo_u32 v122, v116, s11
	v_add_u32_e32 v122, v122, v117
	s_waitcnt lgkmcnt(0)
	v_cvt_pk_bf16_f32 v104, v88, v89
	v_cvt_pk_bf16_f32 v105, v90, v91
	v_cvt_pk_bf16_f32 v106, v92, v93
	v_cvt_pk_bf16_f32 v107, v94, v95
	v_cvt_pk_bf16_f32 v108, v96, v97
	v_cvt_pk_bf16_f32 v109, v98, v99
	v_cvt_pk_bf16_f32 v110, v100, v101
	v_cvt_pk_bf16_f32 v111, v102, v103
	global_store_dwordx4 v122, v[104:107], s[8:9]
	global_store_dwordx4 v122, v[108:111], s[8:9] offset:16
	s_nop 1
	s_waitcnt vmcnt(8)
	ds_write_b32 v114, v72 offset:0
	ds_write_b32 v114, v73 offset:4
	ds_write_b32 v114, v74 offset:8
	ds_write_b32 v114, v75 offset:12
	ds_write_b32 v114, v76 offset:8320
	ds_write_b32 v114, v77 offset:8324
	ds_write_b32 v114, v78 offset:8328
	ds_write_b32 v114, v79 offset:8332
	ds_write_b32 v114, v80 offset:16640
	ds_write_b32 v114, v81 offset:16644
	ds_write_b32 v114, v82 offset:16648
	ds_write_b32 v114, v83 offset:16652
	ds_write_b32 v114, v84 offset:24960
	ds_write_b32 v114, v85 offset:24964
	ds_write_b32 v114, v86 offset:24968
	ds_write_b32 v114, v87 offset:24972
	s_waitcnt lgkmcnt(0)
	s_barrier
	ds_read_b32 v88, v115 offset:0
	ds_read_b32 v89, v115 offset:260
	ds_read_b32 v90, v115 offset:520
	ds_read_b32 v91, v115 offset:780
	ds_read_b32 v92, v115 offset:1040
	ds_read_b32 v93, v115 offset:1300
	ds_read_b32 v94, v115 offset:1560
	ds_read_b32 v95, v115 offset:1820
	ds_read_b32 v96, v115 offset:2080
	ds_read_b32 v97, v115 offset:2340
	ds_read_b32 v98, v115 offset:2600
	ds_read_b32 v99, v115 offset:2860
	ds_read_b32 v100, v115 offset:3120
	ds_read_b32 v101, v115 offset:3380
	ds_read_b32 v102, v115 offset:3640
	ds_read_b32 v103, v115 offset:3900
	s_mul_i32 s48, s85, 2
	s_add_u32 s48, s48, s86
	s_min_u32 s48, s48, s84
	s_sub_u32 s0, s48, 0xe0
	s_mul_i32 s2, s0, 0x4ed
	s_lshr_b32 s2, s2, 17
	s_mul_i32 s3, s2, 0x68
	s_sub_u32 s3, s0, s3
	s_mul_i32 s4, s2, 0x340000
	s_lshl_b32 s0, s3, 8
	s_add_u32 s4, s4, s0
	s_add_u32 s6, s80, s4
	s_addc_u32 s7, s81, 0
	s_lshl_b32 s4, s3, 17
	s_lshl_b32 s0, s2, 8
	s_add_u32 s4, s4, s0
	s_add_u32 s8, s82, s4
	s_addc_u32 s9, s83, 0
	s_movk_i32 s10, 0x6800
	s_movk_i32 s11, 0x800
	v_mul_lo_u32 v122, v116, s11
	v_add_u32_e32 v122, v122, v117
	s_waitcnt lgkmcnt(0)
	v_cvt_pk_bf16_f32 v104, v88, v89
	v_cvt_pk_bf16_f32 v105, v90, v91
	v_cvt_pk_bf16_f32 v106, v92, v93
	v_cvt_pk_bf16_f32 v107, v94, v95
	v_cvt_pk_bf16_f32 v108, v96, v97
	v_cvt_pk_bf16_f32 v109, v98, v99
	v_cvt_pk_bf16_f32 v110, v100, v101
	v_cvt_pk_bf16_f32 v111, v102, v103
	global_store_dwordx4 v122, v[104:107], s[8:9]
	global_store_dwordx4 v122, v[108:111], s[8:9] offset:16
	s_nop 1
	s_waitcnt vmcnt(6)
	ds_write_b32 v114, v124 offset:33792
	ds_write_b32 v114, v125 offset:33796
	ds_write_b32 v114, v126 offset:33800
	ds_write_b32 v114, v127 offset:33804
	ds_write_b32 v114, v128 offset:42112
	ds_write_b32 v114, v129 offset:42116
	ds_write_b32 v114, v130 offset:42120
	ds_write_b32 v114, v131 offset:42124
	ds_write_b32 v114, v132 offset:50432
	ds_write_b32 v114, v133 offset:50436
	ds_write_b32 v114, v134 offset:50440
	ds_write_b32 v114, v135 offset:50444
	ds_write_b32 v114, v136 offset:58752
	ds_write_b32 v114, v137 offset:58756
	ds_write_b32 v114, v138 offset:58760
	ds_write_b32 v114, v139 offset:58764
	s_waitcnt lgkmcnt(0)
	s_barrier
	ds_read_b32 v88, v115 offset:33792
	ds_read_b32 v89, v115 offset:34052
	ds_read_b32 v90, v115 offset:34312
	ds_read_b32 v91, v115 offset:34572
	ds_read_b32 v92, v115 offset:34832
	ds_read_b32 v93, v115 offset:35092
	ds_read_b32 v94, v115 offset:35352
	ds_read_b32 v95, v115 offset:35612
	ds_read_b32 v96, v115 offset:35872
	ds_read_b32 v97, v115 offset:36132
	ds_read_b32 v98, v115 offset:36392
	ds_read_b32 v99, v115 offset:36652
	ds_read_b32 v100, v115 offset:36912
	ds_read_b32 v101, v115 offset:37172
	ds_read_b32 v102, v115 offset:37432
	ds_read_b32 v103, v115 offset:37692
	s_mul_i32 s48, s85, 3
	s_add_u32 s48, s48, s86
	s_min_u32 s48, s48, s84
	s_sub_u32 s0, s48, 0xe0
	s_mul_i32 s2, s0, 0x4ed
	s_lshr_b32 s2, s2, 17
	s_mul_i32 s3, s2, 0x68
	s_sub_u32 s3, s0, s3
	s_mul_i32 s4, s2, 0x340000
	s_lshl_b32 s0, s3, 8
	s_add_u32 s4, s4, s0
	s_add_u32 s6, s80, s4
	s_addc_u32 s7, s81, 0
	s_lshl_b32 s4, s3, 17
	s_lshl_b32 s0, s2, 8
	s_add_u32 s4, s4, s0
	s_add_u32 s8, s82, s4
	s_addc_u32 s9, s83, 0
	s_movk_i32 s10, 0x6800
	s_movk_i32 s11, 0x800
	v_mul_lo_u32 v122, v116, s11
	v_add_u32_e32 v122, v122, v117
	s_waitcnt lgkmcnt(0)
	v_cvt_pk_bf16_f32 v104, v88, v89
	v_cvt_pk_bf16_f32 v105, v90, v91
	v_cvt_pk_bf16_f32 v106, v92, v93
	v_cvt_pk_bf16_f32 v107, v94, v95
	v_cvt_pk_bf16_f32 v108, v96, v97
	v_cvt_pk_bf16_f32 v109, v98, v99
	v_cvt_pk_bf16_f32 v110, v100, v101
	v_cvt_pk_bf16_f32 v111, v102, v103
	global_store_dwordx4 v122, v[104:107], s[8:9]
	global_store_dwordx4 v122, v[108:111], s[8:9] offset:16
	s_nop 1
	s_waitcnt vmcnt(0)
	s_barrier
	s_branch .LBB0_726
